# work-queue slot broadcast via ds_write/ds_read instead of flat LDS accesses
# baseline (speedup 1.0000x reference)
.LBB0_448:
	v_writelane_b32 v254, s0, 14
	s_waitcnt vmcnt(0)
	s_barrier
	v_writelane_b32 v254, s1, 15
	s_and_saveexec_b64 s[0:1], s[34:35]
	s_cbranch_execz .LBB0_450
	s_mov_b64 s[2:3], src_shared_base
	s_add_i32 s2, 0, 0x20008
	s_cmp_lg_u32 s2, -1
	s_cselect_b32 s2, s2, 0
	s_cselect_b32 s3, s3, 0
	v_mov_b32_e32 v2, s2
	v_mov_b32_e32 v3, s3
	ds_write_b32 v2, v163
	s_waitcnt lgkmcnt(0)
.LBB0_450:
	s_or_b64 exec, exec, s[0:1]
	s_mov_b64 s[0:1], src_shared_base
	s_add_i32 s0, 0, 0x20008
	s_cmp_lg_u32 s0, -1
	s_cselect_b32 s0, s0, 0
	s_cselect_b32 s1, s1, 0
	v_mov_b32_e32 v2, s0
	v_mov_b32_e32 v3, s1
	s_waitcnt lgkmcnt(0)
	s_barrier
	ds_read_b32 v159, v2
	s_waitcnt lgkmcnt(0)
	s_movk_i32 s0, 0x4a0
	s_waitcnt lgkmcnt(0)
	v_cmp_gt_i32_e32 vcc, s0, v159
	s_movk_i32 s0, 0x49f
	v_cmp_lt_i32_e64 s[0:1], s0, v159
	s_nop 1
	v_writelane_b32 v254, s0, 16
	s_nop 1
	v_writelane_b32 v254, s1, 17
	s_mov_b64 s[0:1], exec
	v_writelane_b32 v254, s0, 18
	s_nop 1
	v_writelane_b32 v254, s1, 19
	s_and_b64 s[0:1], s[0:1], vcc
	s_mov_b64 exec, s[0:1]
	s_cbranch_execz .LBB0_447
	s_and_saveexec_b64 s[0:1], s[34:35]
	s_cbranch_execz .LBB0_455
	s_mov_b64 s[4:5], exec
	v_mbcnt_lo_u32_b32 v2, s4, 0
	v_mbcnt_hi_u32_b32 v2, s5, v2
	v_cmp_eq_u32_e32 vcc, 0, v2
	s_and_saveexec_b64 s[2:3], vcc
	s_cbranch_execz .LBB0_454
	s_bcnt1_i32_b64 s4, s[4:5]
	v_mov_b32_e32 v3, s4
	global_atomic_add v3, v191, v3, s[28:29] sc0
